# the same norm-weight hoist applied to the layer-start norm and the final norm row loops (deleted instructions replaced by s_nop 0 so every hazard distance is kept)
# speedup vs baseline: 1.0084x; 1.0040x over previous
; __device__ __forceinline__ void store8_wt(void* p, u32x2w v) { asm volatile("global_store_dwordx2 %0, %1, off sc1\n\ts_nop 1" :: "v"(p), "v"(v) : "memory"); }
; __device__ __forceinline__ unsigned pk2(float lo, float hi) { f32x2_t v = {lo, hi}; bf16x2_t b = __builtin_convertvector(v, bf16x2_t); return __builtin_bit_cast(unsigned, b); }
; template <int MODE> __device__ __forceinline__ void norm_phase(const Ptrs& P, const float* nw, int gw, int NGW, int lane) {
;     bf16_t* H = (bf16_t*)(P.ws + WS_H); bf16_t* U = (bf16_t*)(P.ws + WS_U);
;     const int nrows = (MODE == 2) ? MMAIN : MTOK;
;     f32x4 xn[8]; u32x2 hn[8];
;     ...
;     int row = gw;
;     if (row < nrows) NORM_LOAD(row);
;     for (; row < nrows; row += NGW) {
;         f32x4 v[8]; float ss = 0.f;
; #pragma unroll
;         for (int j = 0; j < 8; ++j) v[j] = (MODE == 1) ? xn[j] : (f32x4){bflo(hn[j].x), bfhi(hn[j].x), bflo(hn[j].y), bfhi(hn[j].y)};
;         if (row + NGW < nrows) NORM_LOAD(row + NGW);
; #pragma unroll
;         for (int j = 0; j < 8; ++j) ss += (v[j][0] * v[j][0] + v[j][1] * v[j][1]) + (v[j][2] * v[j][2] + v[j][3] * v[j][3]);
;         ss = wave_sum(ss, lane);
;         const float rstd = 1.0f / sqrtf(ss * (1.0f / DM) + EPS);
;         if (MODE == 1) {
; #pragma unroll
;             for (int j = 0; j < 8; ++j) { u32x2 w; w.x = pk2(v[j][0], v[j][1]); w.y = pk2(v[j][2], v[j][3]); pg8::store8_wt((u32x2*)(H + (size_t)row * DM) + 64 * j + lane, w); }
;         }
; #pragma unroll
;         for (int j = 0; j < 8; ++j) {
;             const f32x4 w4 = ((const f32x4*)nw)[64 * j + lane];
.LBB0_138:
	s_or_b64 exec, exec, s[4:5]
	s_getreg_b32 s3, hwreg(HW_REG_HW_ID, 0, 6)
	s_and_b32 s3, s3, 63
	s_lshl_b32 s3, s3, 2
	s_add_i32 s3, s3, 0
	s_add_i32 s3, s3, 0x27ef0
	v_mov_b32_e32 v0, s3
	ds_read_b32 v0, v0
	s_mov_b64 s[6:7], s[0:1]
	v_readlane_b32 s8, v255, 36
	v_readlane_b32 s9, v255, 37
	s_mov_b64 s[4:5], -1
	s_waitcnt lgkmcnt(0)
	v_readfirstlane_b32 s3, v0
	s_and_b64 vcc, exec, s[8:9]
	s_nop 0
	v_lshl_add_u32 v0, s3, 6, v213
	global_load_dwordx2 v[26:27], v16, s[6:7] offset:32
	global_load_dwordx2 v[28:29], v16, s[6:7] offset:184
	v_ashrrev_i32_e32 v17, 6, v0
	v_readlane_b32 s3, v255, 18
	v_and_b32_e32 v30, 63, v0
	s_nop 0
	v_add_u32_e32 v70, s3, v17
	s_mov_b32 s3, 0x8020
	v_cmp_gt_i32_e64 s[36:37], s3, v70
	s_cbranch_vccz .LBB0_145
	s_and_saveexec_b64 s[4:5], s[36:37]
	s_cbranch_execz .LBB0_144
	s_waitcnt vmcnt(2)
	v_ashrrev_i32_e32 v71, 31, v70
	v_lshlrev_b64 v[18:19], 12, v[70:71]
	s_waitcnt vmcnt(0)
	v_lshl_add_u64 v[0:1], v[28:29], 0, v[18:19]
	v_lshlrev_b32_e32 v20, 3, v30
	v_mov_b32_e32 v21, v16
	v_lshl_add_u64 v[0:1], v[0:1], 0, v[20:21]
	s_mov_b64 s[8:9], 0x100000
	v_lshl_add_u64 v[2:3], v[0:1], 0, s[8:9]
	v_add_co_u32_e32 v0, vcc, 0x100000, v0
	global_load_dwordx2 v[46:47], v[2:3], off offset:2560
	global_load_dwordx2 v[48:49], v[2:3], off offset:3072
	global_load_dwordx2 v[52:53], v[2:3], off offset:512
	global_load_dwordx2 v[44:45], v[2:3], off offset:1024
	global_load_dwordx2 v[42:43], v[2:3], off offset:1536
	global_load_dwordx2 v[50:51], v[2:3], off offset:2048
	v_addc_co_u32_e32 v1, vcc, 0, v1, vcc
	global_load_dwordx2 v[62:63], v[2:3], off offset:3584
	global_load_dwordx2 v[54:55], v[0:1], off
	s_mov_b64 s[8:9], 0x2000
	v_lshlrev_b32_e32 v2, 4, v30
	v_or_b32_e32 v18, v18, v20
	v_lshl_add_u64 v[14:15], v[26:27], 0, s[8:9]
	v_lshlrev_b32_e32 v0, 2, v30
	v_mov_b32_e32 v3, v16
	v_mov_b32_e32 v5, v16
	v_mov_b32_e32 v7, v16
	v_mov_b32_e32 v9, v16
	v_mov_b32_e32 v11, v16
	v_mov_b32_e32 v13, v16
	v_mov_b32_e32 v23, v16
	v_mov_b32_e32 v25, v16
	v_or_b32_e32 v4, 0x400, v2
	v_or_b32_e32 v6, 0x800, v2
	v_or_b32_e32 v8, 0xc00, v2
	v_or_b32_e32 v10, 0x1000, v2
	v_or_b32_e32 v12, 0x1400, v2
	v_or_b32_e32 v22, 0x1800, v2
	v_or_b32_e32 v24, 0x1c00, v2
	v_lshl_add_u64 v[18:19], v[28:29], 0, v[18:19]
	s_mov_b64 s[10:11], 0x10300000
	s_mov_b64 s[8:9], 0
	v_mov_b32_e32 v31, v70
	v_xor_b32_e32 v64, 4, v0
	v_xor_b32_e32 v65, 8, v0
	v_xor_b32_e32 v66, 16, v0
	v_xor_b32_e32 v67, 32, v0
	v_xor_b32_e32 v68, 64, v0
	v_xor_b32_e32 v69, 0x80, v0
	v_lshl_add_u64 v[0:1], v[14:15], 0, v[2:3]
	v_lshl_add_u64 v[2:3], v[14:15], 0, v[4:5]
	v_lshl_add_u64 v[4:5], v[14:15], 0, v[6:7]
	v_lshl_add_u64 v[6:7], v[14:15], 0, v[8:9]
	v_lshl_add_u64 v[8:9], v[14:15], 0, v[10:11]
	v_lshl_add_u64 v[10:11], v[14:15], 0, v[12:13]
	v_lshl_add_u64 v[12:13], v[14:15], 0, v[22:23]
	v_lshl_add_u64 v[14:15], v[14:15], 0, v[24:25]
	v_lshl_add_u64 v[18:19], v[18:19], 0, s[10:11]
	s_waitcnt vmcnt(7)
	v_mov_b64_e32 v[24:25], v[46:47]
	s_waitcnt vmcnt(6)
	v_mov_b64_e32 v[22:23], v[48:49]
	s_waitcnt vmcnt(5)
	v_mov_b64_e32 v[38:39], v[52:53]
	s_waitcnt vmcnt(4)
	v_mov_b64_e32 v[36:37], v[44:45]
	s_waitcnt vmcnt(3)
	v_mov_b64_e32 v[34:35], v[42:43]
	s_waitcnt vmcnt(2)
	v_mov_b64_e32 v[32:33], v[50:51]
	s_waitcnt vmcnt(1)
	v_mov_b64_e32 v[40:41], v[62:63]
	s_waitcnt vmcnt(0)
	v_mov_b64_e32 v[20:21], v[54:55]
	global_load_dwordx4 v[128:131], v[0:1], off
	global_load_dwordx4 v[132:135], v[2:3], off
	global_load_dwordx4 v[136:139], v[4:5], off
	global_load_dwordx4 v[140:143], v[6:7], off
	global_load_dwordx4 v[144:147], v[8:9], off
	global_load_dwordx4 v[148:151], v[10:11], off
	global_load_dwordx4 v[152:155], v[12:13], off
	global_load_dwordx4 v[156:159], v[14:15], off
	s_waitcnt vmcnt(0)
	s_branch .LBB0_142
.LBB0_141:
	s_or_b64 exec, exec, s[10:11]
	v_and_b32_e32 v79, 0xffff0000, v54
	v_and_b32_e32 v78, 0xffff0000, v52
	v_and_b32_e32 v83, 0xffff0000, v55
	v_and_b32_e32 v82, 0xffff0000, v53
	v_lshlrev_b32_e32 v77, 16, v54
	v_lshlrev_b32_e32 v76, 16, v52
	v_lshlrev_b32_e32 v81, 16, v55
	v_lshlrev_b32_e32 v80, 16, v53
	v_lshlrev_b32_e32 v85, 16, v45
	v_lshlrev_b32_e32 v84, 16, v44
	v_and_b32_e32 v87, 0xffff0000, v45
	v_and_b32_e32 v86, 0xffff0000, v44
	v_lshlrev_b32_e32 v58, 16, v42
	v_and_b32_e32 v59, 0xffff0000, v42
	v_lshlrev_b32_e32 v42, 16, v62
	v_and_b32_e32 v92, 0xffff0000, v62
	v_lshlrev_b32_e32 v44, 16, v63
	v_and_b32_e32 v45, 0xffff0000, v63
	v_pk_mul_f32 v[62:63], v[78:79], v[78:79]
	v_pk_mul_f32 v[72:73], v[82:83], v[82:83]
	v_pk_fma_f32 v[62:63], v[76:77], v[76:77], v[62:63]
	v_pk_fma_f32 v[72:73], v[80:81], v[80:81], v[72:73]
	v_lshlrev_b32_e32 v60, 16, v43
	v_pk_add_f32 v[62:63], v[62:63], v[72:73]
	v_lshlrev_b32_e32 v54, 16, v50
	v_pk_add_f32 v[62:63], v[62:63], v[62:63] op_sel_hi:[0,1]
	v_pk_mul_f32 v[72:73], v[86:87], v[86:87]
	v_and_b32_e32 v61, 0xffff0000, v43
	v_pk_fma_f32 v[72:73], v[84:85], v[84:85], v[72:73]
	v_mul_f32_e32 v55, v58, v58
	v_mul_f32_e32 v75, v59, v59
	v_mul_f32_e32 v62, v60, v60
	v_mov_b32_e32 v74, v54
	v_and_b32_e32 v71, 0xffff0000, v50
	v_lshlrev_b32_e32 v56, 16, v51
	v_and_b32_e32 v57, 0xffff0000, v51
	v_pk_add_f32 v[72:73], v[72:73], v[72:73] op_sel_hi:[0,1]
	v_pk_fma_f32 v[88:89], v[60:61], v[60:61], v[62:63] op_sel_hi:[1,1,0]
	v_pk_add_f32 v[74:75], v[54:55], v[74:75]
	v_mul_f32_e32 v88, v71, v71
	v_mul_f32_e32 v72, v56, v56
	v_mul_f32_e32 v62, v57, v57
	v_mul_f32_e32 v90, v54, v54
	v_mov_b32_e32 v91, v75
	v_pk_add_f32 v[74:75], v[90:91], v[88:89]
	v_pk_add_f32 v[62:63], v[72:73], v[62:63]
	v_and_b32_e32 v51, 0xffff0000, v47
	v_and_b32_e32 v50, 0xffff0000, v46
	v_pk_add_f32 v[62:63], v[74:75], v[62:63]
	v_lshlrev_b32_e32 v53, 16, v47
	v_lshlrev_b32_e32 v52, 16, v46
	v_lshlrev_b32_e32 v46, 16, v48
	v_and_b32_e32 v47, 0xffff0000, v48
	v_lshlrev_b32_e32 v48, 16, v49
	v_pk_add_f32 v[62:63], v[62:63], v[62:63] op_sel_hi:[0,1]
	v_pk_mul_f32 v[72:73], v[50:51], v[50:51]
	v_and_b32_e32 v49, 0xffff0000, v49
	v_pk_fma_f32 v[72:73], v[52:53], v[52:53], v[72:73]
	v_mul_f32_e32 v43, v46, v46
	v_mul_f32_e32 v75, v47, v47
	v_mul_f32_e32 v62, v48, v48
	v_mov_b32_e32 v74, v42
	v_pk_add_f32 v[72:73], v[72:73], v[72:73] op_sel_hi:[0,1]
	v_pk_fma_f32 v[88:89], v[48:49], v[48:49], v[62:63] op_sel_hi:[1,1,0]
	v_pk_add_f32 v[74:75], v[42:43], v[74:75]
	v_mul_f32_e32 v88, v92, v92
	v_mul_f32_e32 v72, v44, v44
	v_mul_f32_e32 v62, v45, v45
	v_mul_f32_e32 v90, v42, v42
	v_mov_b32_e32 v91, v75
	v_pk_add_f32 v[74:75], v[90:91], v[88:89]
	v_pk_add_f32 v[62:63], v[72:73], v[62:63]
	v_mov_b32_e32 v90, v81
	v_pk_add_f32 v[62:63], v[74:75], v[62:63]
	s_nop 0
	v_add_f32_e32 v43, v62, v63
	ds_bpermute_b32 v55, v64, v43
	v_mov_b32_e32 v91, v83
	v_mov_b32_e32 v81, v82
	v_add_u32_e32 v31, 0x800, v31
	s_waitcnt lgkmcnt(0)
; __device__ __forceinline__ void store8_wt(void* p, u32x2w v) { asm volatile("global_store_dwordx2 %0, %1, off sc1\n\ts_nop 1" :: "v"(p), "v"(v) : "memory"); }
; __device__ __forceinline__ unsigned pk2(float lo, float hi) { f32x2_t v = {lo, hi}; bf16x2_t b = __builtin_convertvector(v, bf16x2_t); return __builtin_bit_cast(unsigned, b); }
; __device__ __forceinline__ float shx(float v, int o, int lane) { return __builtin_bit_cast(float, __builtin_amdgcn_ds_bpermute((lane ^ o) << 2, __builtin_bit_cast(int, v))); }
; __device__ __forceinline__ float wave_sum(float v, int lane) {
; #pragma unroll
;     for (int o = 1; o < 64; o <<= 1) v += shx(v, o, lane);
;     return v;
; }
; template <int MODE> __device__ __forceinline__ void norm_phase(const Ptrs& P, const float* nw, int gw, int NGW, int lane) {
;     ...
;         for (int j = 0; j < 8; ++j) ss += (v[j][0] * v[j][0] + v[j][1] * v[j][1]) + (v[j][2] * v[j][2] + v[j][3] * v[j][3]);
;         ss = wave_sum(ss, lane);
;         const float rstd = 1.0f / sqrtf(ss * (1.0f / DM) + EPS);
;         if (MODE == 1) {
; #pragma unroll
;             for (int j = 0; j < 8; ++j) { u32x2 w; w.x = pk2(v[j][0], v[j][1]); w.y = pk2(v[j][2], v[j][3]); pg8::store8_wt((u32x2*)(H + (size_t)row * DM) + 64 * j + lane, w); }
;         }
; #pragma unroll
;         for (int j = 0; j < 8; ++j) {
;             const f32x4 w4 = ((const f32x4*)nw)[64 * j + lane];
;             const f32x4 o = v[j] * rstd * w4;
;             if (MODE == 2) ((f32x4*)(P.out + (size_t)row * DM))[64 * j + lane] = o;
;             else { u32x2 w; w.x = pk2(o[0], o[1]); w.y = pk2(o[2], o[3]); pg8::store8_wt((u32x2*)(U + (size_t)row * DM) + 64 * j + lane, w); }
;         }
	v_add_f32_e32 v43, v43, v55
	ds_bpermute_b32 v55, v65, v43
	s_waitcnt lgkmcnt(0)
	v_add_f32_e32 v43, v43, v55
	ds_bpermute_b32 v55, v66, v43
	s_waitcnt lgkmcnt(0)
	v_add_f32_e32 v43, v43, v55
	ds_bpermute_b32 v55, v67, v43
	s_waitcnt lgkmcnt(0)
	v_add_f32_e32 v43, v43, v55
	ds_bpermute_b32 v55, v68, v43
	s_waitcnt lgkmcnt(0)
	v_add_f32_e32 v43, v43, v55
	ds_bpermute_b32 v55, v69, v43
	s_waitcnt lgkmcnt(0)
	v_add_f32_e32 v43, v43, v55
	v_fmamk_f32 v43, v43, 0x3a000000, v234
	v_mul_f32_e32 v55, 0x4f800000, v43
	v_cmp_gt_f32_e32 vcc, s17, v43
	s_nop 1
	v_cndmask_b32_e32 v43, v43, v55, vcc
	v_sqrt_f32_e32 v55, v43
	s_nop 0
	v_add_u32_e32 v62, -1, v55
	v_fma_f32 v63, -v62, v55, v43
	v_cmp_ge_f32_e64 s[36:37], 0, v63
	v_add_u32_e32 v63, 1, v55
	s_nop 0
	v_cndmask_b32_e64 v62, v55, v62, s[36:37]
	v_fma_f32 v55, -v63, v55, v43
	v_cmp_lt_f32_e64 s[36:37], 0, v55
	s_nop 1
	v_cndmask_b32_e64 v55, v62, v63, s[36:37]
	v_mul_f32_e32 v62, 0x37800000, v55
	v_cndmask_b32_e32 v55, v55, v62, vcc
	v_cmp_class_f32_e32 vcc, v43, v235
	s_nop 1
	v_cndmask_b32_e32 v43, v55, v43, vcc
	v_div_scale_f32 v55, s[10:11], v43, v43, 1.0
	v_rcp_f32_e32 v62, v55
	s_mov_b64 s[10:11], 0x200
	v_fma_f32 v63, -v55, v62, 1.0
	v_fmac_f32_e32 v62, v63, v62
	v_div_scale_f32 v63, vcc, 1.0, v43, 1.0
	v_mul_f32_e32 v88, v63, v62
	v_fma_f32 v89, -v55, v88, v63
	v_fmac_f32_e32 v88, v89, v62
	v_fma_f32 v55, -v55, v88, v63
	v_div_fmas_f32 v55, v55, v62, v88
	v_div_fixup_f32 v88, v55, v43, 1.0
	v_mov_b32_e32 v62, v77
	v_mov_b32_e32 v63, v79
	v_pk_mul_f32 v[62:63], v[62:63], v[88:89] op_sel_hi:[1,0]
	v_pk_mul_f32 v[90:91], v[90:91], v[88:89] op_sel_hi:[1,0]
	s_nop 0
	v_pk_mul_f32 v[62:63], v[128:129], v[62:63]
	v_pk_mul_f32 v[74:75], v[130:131], v[90:91]
	v_cvt_pk_bf16_f32 v62, v62, v63
	v_cvt_pk_bf16_f32 v63, v74, v75
	global_store_dwordx2 v[18:19], v[62:63], off sc1
	s_nop 1
	s_nop 0
	v_mov_b32_e32 v77, v78
	v_pk_mul_f32 v[76:77], v[76:77], v[88:89] op_sel_hi:[1,0]
	v_pk_mul_f32 v[78:79], v[80:81], v[88:89] op_sel_hi:[1,0]
	v_lshl_add_u64 v[62:63], v[18:19], 0, s[10:11]
	s_mov_b64 s[10:11], 0x400
	v_pk_mul_f32 v[58:59], v[58:59], v[88:89] op_sel_hi:[1,0]
	v_pk_mul_f32 v[60:61], v[60:61], v[88:89] op_sel_hi:[1,0]
	v_mov_b32_e32 v55, v71
	v_pk_mul_f32 v[54:55], v[54:55], v[88:89] op_sel_hi:[1,0]
	v_pk_mul_f32 v[56:57], v[56:57], v[88:89] op_sel_hi:[1,0]
	v_pk_mul_f32 v[46:47], v[46:47], v[88:89] op_sel_hi:[1,0]
	v_pk_mul_f32 v[48:49], v[48:49], v[88:89] op_sel_hi:[1,0]
	v_mov_b32_e32 v43, v92
	v_pk_mul_f32 v[42:43], v[42:43], v[88:89] op_sel_hi:[1,0]
	v_pk_mul_f32 v[44:45], v[44:45], v[88:89] op_sel_hi:[1,0]
	s_nop 0
	v_pk_mul_f32 v[74:75], v[134:135], v[78:79]
	v_pk_mul_f32 v[72:73], v[132:133], v[76:77]
	v_mov_b32_e32 v76, v84
	v_cvt_pk_bf16_f32 v72, v72, v73
	v_cvt_pk_bf16_f32 v73, v74, v75
	global_store_dwordx2 v[62:63], v[72:73], off sc1
	s_nop 1
	s_nop 0
	v_mov_b32_e32 v77, v86
	v_mov_b32_e32 v86, v85
	v_pk_mul_f32 v[76:77], v[88:89], v[76:77] op_sel_hi:[0,1]
	v_pk_mul_f32 v[78:79], v[88:89], v[86:87] op_sel_hi:[0,1]
	v_lshl_add_u64 v[62:63], v[18:19], 0, s[10:11]
	s_mov_b64 s[10:11], 0x600
	s_nop 0
	v_pk_mul_f32 v[74:75], v[138:139], v[78:79]
	v_pk_mul_f32 v[72:73], v[136:137], v[76:77]
	s_nop 0
	v_cvt_pk_bf16_f32 v72, v72, v73
	v_cvt_pk_bf16_f32 v73, v74, v75
	global_store_dwordx2 v[62:63], v[72:73], off sc1
	s_nop 1
	s_nop 0
	v_lshl_add_u64 v[62:63], v[18:19], 0, s[10:11]
	s_mov_b64 s[10:11], 0x800
	s_nop 0
	v_pk_mul_f32 v[60:61], v[142:143], v[60:61]
	v_pk_mul_f32 v[58:59], v[140:141], v[58:59]
	s_nop 0
	v_cvt_pk_bf16_f32 v58, v58, v59
	v_cvt_pk_bf16_f32 v59, v60, v61
	global_store_dwordx2 v[62:63], v[58:59], off sc1
	s_nop 1
	s_nop 0
	v_lshl_add_u64 v[62:63], v[18:19], 0, s[10:11]
	s_mov_b64 s[10:11], 0xa00
	s_nop 0
	v_pk_mul_f32 v[56:57], v[56:57], v[146:147]
	v_pk_mul_f32 v[54:55], v[54:55], v[144:145]
	v_mov_b32_e32 v60, v52
	v_cvt_pk_bf16_f32 v54, v54, v55
	v_cvt_pk_bf16_f32 v55, v56, v57
	global_store_dwordx2 v[62:63], v[54:55], off sc1
	s_nop 1
	s_nop 0
	v_mov_b32_e32 v61, v50
	v_mov_b32_e32 v50, v53
	v_pk_mul_f32 v[52:53], v[88:89], v[60:61] op_sel_hi:[0,1]
	v_pk_mul_f32 v[50:51], v[88:89], v[50:51] op_sel_hi:[0,1]
	v_lshl_add_u64 v[58:59], v[18:19], 0, s[10:11]
	s_mov_b64 s[10:11], 0xc00
	s_waitcnt vmcnt(5)
	v_mov_b64_e32 v[62:63], v[40:41]
	s_nop 0
	v_pk_mul_f32 v[50:51], v[50:51], v[150:151]
	v_pk_mul_f32 v[52:53], v[52:53], v[148:149]
	v_lshl_add_u64 v[54:55], v[18:19], 0, s[10:11]
	v_cvt_pk_bf16_f32 v52, v52, v53
	v_cvt_pk_bf16_f32 v53, v50, v51
	global_store_dwordx2 v[58:59], v[52:53], off sc1
	s_nop 1
	s_nop 0
	s_mov_b64 s[10:11], 0xe00
	v_lshl_add_u64 v[56:57], v[18:19], 0, s[10:11]
	s_mov_b64 s[10:11], 0x800000
	v_lshl_add_u64 v[18:19], v[18:19], 0, s[10:11]
	s_nop 0
	v_pk_mul_f32 v[48:49], v[48:49], v[154:155]
	v_pk_mul_f32 v[46:47], v[46:47], v[152:153]
	v_mov_b64_e32 v[50:51], v[32:33]
	v_cvt_pk_bf16_f32 v46, v46, v47
	v_cvt_pk_bf16_f32 v47, v48, v49
	global_store_dwordx2 v[54:55], v[46:47], off sc1
	s_nop 1
	s_nop 0
	v_mov_b64_e32 v[48:49], v[22:23]
	v_mov_b64_e32 v[46:47], v[24:25]
	s_nop 0
	v_pk_mul_f32 v[44:45], v[44:45], v[158:159]
	v_pk_mul_f32 v[42:43], v[42:43], v[156:157]
	v_mov_b64_e32 v[52:53], v[38:39]
	v_cvt_pk_bf16_f32 v42, v42, v43
	v_cvt_pk_bf16_f32 v43, v44, v45
	global_store_dwordx2 v[56:57], v[42:43], off sc1
	s_nop 1
	v_mov_b64_e32 v[42:43], v[34:35]
	v_mov_b64_e32 v[44:45], v[36:37]
	v_mov_b64_e32 v[54:55], v[20:21]
	s_andn2_b64 exec, exec, s[8:9]
	s_cbranch_execz .LBB0_144

; __device__ __forceinline__ void store8_wt(void* p, u32x2w v) { asm volatile("global_store_dwordx2 %0, %1, off sc1\n\ts_nop 1" :: "v"(p), "v"(v) : "memory"); }
; __device__ __forceinline__ unsigned pk2(float lo, float hi) { f32x2_t v = {lo, hi}; bf16x2_t b = __builtin_convertvector(v, bf16x2_t); return __builtin_bit_cast(unsigned, b); }
; template <int MODE> __device__ __forceinline__ void norm_phase(const Ptrs& P, const float* nw, int gw, int NGW, int lane) {
;     bf16_t* H = (bf16_t*)(P.ws + WS_H); bf16_t* U = (bf16_t*)(P.ws + WS_U);
;     const int nrows = (MODE == 2) ? MMAIN : MTOK;
;     f32x4 xn[8]; u32x2 hn[8];
;     ...
;     int row = gw;
;     if (row < nrows) NORM_LOAD(row);
;     for (; row < nrows; row += NGW) {
;         f32x4 v[8]; float ss = 0.f;
; #pragma unroll
;         for (int j = 0; j < 8; ++j) v[j] = (MODE == 1) ? xn[j] : (f32x4){bflo(hn[j].x), bfhi(hn[j].x), bflo(hn[j].y), bfhi(hn[j].y)};
;         if (row + NGW < nrows) NORM_LOAD(row + NGW);
; #pragma unroll
;         for (int j = 0; j < 8; ++j) ss += (v[j][0] * v[j][0] + v[j][1] * v[j][1]) + (v[j][2] * v[j][2] + v[j][3] * v[j][3]);
;         ss = wave_sum(ss, lane);
;         const float rstd = 1.0f / sqrtf(ss * (1.0f / DM) + EPS);
;         if (MODE == 1) {
; #pragma unroll
;             for (int j = 0; j < 8; ++j) { u32x2 w; w.x = pk2(v[j][0], v[j][1]); w.y = pk2(v[j][2], v[j][3]); pg8::store8_wt((u32x2*)(H + (size_t)row * DM) + 64 * j + lane, w); }
;         }
; #pragma unroll
;         for (int j = 0; j < 8; ++j) {
;             const f32x4 w4 = ((const f32x4*)nw)[64 * j + lane];
.LBB0_1713:
	s_getreg_b32 s2, hwreg(HW_REG_HW_ID, 0, 6)
	s_and_b32 s2, s2, 63
	s_lshl_b32 s2, s2, 2
	s_add_i32 s2, s2, 0
	s_add_i32 s2, s2, 0x27ef0
	v_mov_b32_e32 v0, s2
	ds_read_b32 v0, v0
	s_waitcnt lgkmcnt(0)
	v_readfirstlane_b32 s2, v0
	s_nop 1
	v_lshl_add_u32 v1, s2, 6, v213
	v_readlane_b32 s2, v255, 18
	v_ashrrev_i32_e32 v0, 6, v1
	s_nop 0
	v_add_u32_e32 v0, s2, v0
	s_mov_b32 s2, 0x8000
	v_cmp_gt_i32_e32 vcc, s2, v0
	s_and_saveexec_b64 s[2:3], vcc
	s_cbranch_execz .LBB0_1718
	v_mov_b32_e32 v17, 0
	global_load_dwordx4 v[12:15], v17, s[0:1] offset:176
	global_load_dwordx2 v[10:11], v17, s[0:1] offset:168
	v_and_b32_e32 v6, 63, v1
	v_ashrrev_i32_e32 v1, 31, v0
	v_lshlrev_b64 v[18:19], 12, v[0:1]
	v_lshlrev_b32_e32 v16, 3, v6
	s_mov_b64 s[2:3], 0x100000
	v_lshlrev_b64 v[22:23], 13, v[0:1]
	s_mov_b64 s[0:1], 0x900000
	v_mov_b32_e32 v7, v17
	v_mov_b32_e32 v9, v17
	v_mov_b32_e32 v21, v17
	s_mov_b64 s[4:5], 0
	s_movk_i32 s10, 0x7800
	s_movk_i32 s11, 0x77ff
	v_mov_b32_e32 v64, 0x358637bd
	s_mov_b32 s12, 0xf800000
	v_mov_b32_e32 v65, 0x260
	s_mov_b64 s[6:7], 0x800000
	s_mov_b64 s[8:9], 0x1000000
	s_waitcnt vmcnt(1)
	v_lshl_add_u64 v[2:3], v[14:15], 0, v[18:19]
	v_lshl_add_u64 v[2:3], v[2:3], 0, v[16:17]
	v_lshl_add_u64 v[4:5], v[2:3], 0, s[2:3]
	v_add_co_u32_e32 v2, vcc, 0x100000, v2
	global_load_dwordx2 v[32:33], v[4:5], off offset:2560
	global_load_dwordx2 v[34:35], v[4:5], off offset:3072
	global_load_dwordx2 v[46:47], v[4:5], off offset:512
	global_load_dwordx2 v[38:39], v[4:5], off offset:1024
	global_load_dwordx2 v[36:37], v[4:5], off offset:1536
	global_load_dwordx2 v[62:63], v[4:5], off offset:2048
	v_addc_co_u32_e32 v3, vcc, 0, v3, vcc
	global_load_dwordx2 v[44:45], v[4:5], off offset:3584
	global_load_dwordx2 v[40:41], v[2:3], off
	v_lshlrev_b32_e32 v2, 4, v6
	v_lshlrev_b32_e32 v4, 2, v6
	v_or_b32_e32 v22, v22, v2
	v_or_b32_e32 v18, v18, v16
	s_mov_b64 s[2:3], 0x1000
	v_mov_b32_e32 v3, v17
	v_mov_b32_e32 v5, v17
	v_xor_b32_e32 v1, 4, v4
	v_xor_b32_e32 v66, 8, v4
	v_xor_b32_e32 v67, 16, v4
	v_xor_b32_e32 v68, 32, v4
	v_xor_b32_e32 v69, 64, v4
	v_xor_b32_e32 v70, 0x80, v4
	v_or_b32_e32 v4, 0x1000, v2
	v_or_b32_e32 v6, 0x1400, v2
	v_or_b32_e32 v8, 0x1800, v2
	v_or_b32_e32 v20, 0x1c00, v2
	v_lshl_add_u64 v[12:13], v[12:13], 0, v[22:23]
	v_lshl_add_u64 v[14:15], v[14:15], 0, v[18:19]
	s_waitcnt vmcnt(8)
	v_lshl_add_u64 v[2:3], v[10:11], 0, v[2:3]
	v_lshl_add_u64 v[4:5], v[10:11], 0, v[4:5]
	v_lshl_add_u64 v[6:7], v[10:11], 0, v[6:7]
	v_lshl_add_u64 v[8:9], v[10:11], 0, v[8:9]
	v_lshl_add_u64 v[10:11], v[10:11], 0, v[20:21]
	v_lshl_add_u64 v[12:13], v[12:13], 0, s[2:3]
	v_lshl_add_u64 v[14:15], v[14:15], 0, s[0:1]
	s_waitcnt vmcnt(7)
	v_mov_b64_e32 v[18:19], v[32:33]
	s_waitcnt vmcnt(6)
	v_mov_b64_e32 v[16:17], v[34:35]
	s_waitcnt vmcnt(5)
	v_mov_b64_e32 v[26:27], v[46:47]
	s_waitcnt vmcnt(4)
	v_mov_b64_e32 v[24:25], v[38:39]
	s_waitcnt vmcnt(3)
	v_mov_b64_e32 v[22:23], v[36:37]
	s_waitcnt vmcnt(2)
	v_mov_b64_e32 v[20:21], v[62:63]
	s_waitcnt vmcnt(1)
	v_mov_b64_e32 v[30:31], v[44:45]
	s_waitcnt vmcnt(0)
	v_mov_b64_e32 v[28:29], v[40:41]
	global_load_dwordx4 v[100:103], v[2:3], off
	global_load_dwordx4 v[104:107], v[2:3], off offset:1024
	global_load_dwordx4 v[108:111], v[2:3], off offset:2048
	global_load_dwordx4 v[112:115], v[2:3], off offset:3072
	global_load_dwordx4 v[116:119], v[4:5], off
	global_load_dwordx4 v[120:123], v[6:7], off
	global_load_dwordx4 v[124:127], v[8:9], off
	global_load_dwordx4 v[128:131], v[10:11], off
	s_waitcnt vmcnt(0)
	s_branch .LBB0_1716
.LBB0_1715:
	s_or_b64 exec, exec, s[2:3]
	v_and_b32_e32 v57, 0xffff0000, v40
	v_and_b32_e32 v56, 0xffff0000, v46
	v_and_b32_e32 v77, 0xffff0000, v41
	v_and_b32_e32 v76, 0xffff0000, v47
	v_lshlrev_b32_e32 v55, 16, v40
	v_lshlrev_b32_e32 v54, 16, v46
	v_lshlrev_b32_e32 v61, 16, v41
	v_lshlrev_b32_e32 v60, 16, v47
	v_pk_mul_f32 v[40:41], v[56:57], v[56:57]
	v_pk_mul_f32 v[42:43], v[76:77], v[76:77]
	v_lshlrev_b32_e32 v46, 16, v36
	v_and_b32_e32 v47, 0xffff0000, v36
	v_lshlrev_b32_e32 v48, 16, v37
	v_pk_fma_f32 v[40:41], v[54:55], v[54:55], v[40:41]
	v_pk_fma_f32 v[42:43], v[60:61], v[60:61], v[42:43]
	v_and_b32_e32 v71, 0xffff0000, v62
	v_lshlrev_b32_e32 v62, 16, v62
	v_and_b32_e32 v49, 0xffff0000, v37
	v_pk_add_f32 v[40:41], v[40:41], v[42:43]
	v_lshlrev_b32_e32 v58, 16, v63
	v_and_b32_e32 v59, 0xffff0000, v63
	v_mul_f32_e32 v63, v46, v46
	v_mul_f32_e32 v42, v48, v48
	v_mul_f32_e32 v73, v47, v47
	v_mov_b32_e32 v72, v62
	v_pk_fma_f32 v[42:43], v[48:49], v[48:49], v[42:43] op_sel_hi:[1,1,0]
	v_pk_add_f32 v[72:73], v[62:63], v[72:73]
	v_and_b32_e32 v53, 0xffff0000, v39
	v_and_b32_e32 v52, 0xffff0000, v38
	v_mul_f32_e32 v42, v71, v71
	v_mul_f32_e32 v72, v62, v62
	v_lshlrev_b32_e32 v51, 16, v39
	v_lshlrev_b32_e32 v50, 16, v38
	v_pk_add_f32 v[42:43], v[72:73], v[42:43]
	v_pk_mul_f32 v[72:73], v[52:53], v[52:53]
	v_pk_add_f32 v[40:41], v[40:41], v[40:41] op_sel_hi:[0,1]
	v_pk_fma_f32 v[72:73], v[50:51], v[50:51], v[72:73]
	v_mul_f32_e32 v40, v59, v59
	v_pk_add_f32 v[72:73], v[72:73], v[72:73] op_sel_hi:[0,1]
	v_mul_f32_e32 v72, v58, v58
	v_pk_add_f32 v[40:41], v[72:73], v[40:41]
	v_lshlrev_b32_e32 v37, 16, v33
	v_lshlrev_b32_e32 v36, 16, v32
	v_and_b32_e32 v39, 0xffff0000, v33
	v_and_b32_e32 v38, 0xffff0000, v32
	v_lshlrev_b32_e32 v32, 16, v34
	v_and_b32_e32 v33, 0xffff0000, v34
	v_lshlrev_b32_e32 v34, 16, v35
	v_pk_add_f32 v[72:73], v[42:43], v[40:41]
	v_lshlrev_b32_e32 v42, 16, v44
	v_and_b32_e32 v35, 0xffff0000, v35
	v_and_b32_e32 v79, 0xffff0000, v44
	v_mul_f32_e32 v43, v32, v32
	v_mul_f32_e32 v44, v34, v34
	v_mul_f32_e32 v75, v33, v33
	v_mov_b32_e32 v74, v42
	v_lshlrev_b32_e32 v40, 16, v45
	v_and_b32_e32 v41, 0xffff0000, v45
	v_pk_fma_f32 v[44:45], v[34:35], v[34:35], v[44:45] op_sel_hi:[1,1,0]
	v_pk_add_f32 v[74:75], v[42:43], v[74:75]
	v_mul_f32_e32 v44, v79, v79
	v_mul_f32_e32 v74, v42, v42
	v_pk_add_f32 v[44:45], v[74:75], v[44:45]
	v_pk_mul_f32 v[74:75], v[38:39], v[38:39]
	v_pk_add_f32 v[72:73], v[72:73], v[72:73] op_sel_hi:[0,1]
	v_pk_fma_f32 v[74:75], v[36:37], v[36:37], v[74:75]
	v_mul_f32_e32 v72, v41, v41
	v_pk_add_f32 v[74:75], v[74:75], v[74:75] op_sel_hi:[0,1]
	v_mul_f32_e32 v74, v40, v40
	v_pk_add_f32 v[72:73], v[74:75], v[72:73]
	v_mov_b32_e32 v81, v77
	v_pk_add_f32 v[44:45], v[44:45], v[72:73]
	s_nop 0
	v_add_f32_e32 v43, v44, v45
	ds_bpermute_b32 v44, v1, v43
	s_and_b64 s[0:1], exec, s[0:1]
	v_add_u32_e32 v0, 0x800, v0
	v_lshl_add_u64 v[14:15], v[14:15], 0, s[6:7]
	s_or_b64 s[4:5], s[0:1], s[4:5]
	s_waitcnt lgkmcnt(0)
; __device__ __forceinline__ void store8_wt(void* p, u32x2w v) { asm volatile("global_store_dwordx2 %0, %1, off sc1\n\ts_nop 1" :: "v"(p), "v"(v) : "memory"); }
; __device__ __forceinline__ unsigned pk2(float lo, float hi) { f32x2_t v = {lo, hi}; bf16x2_t b = __builtin_convertvector(v, bf16x2_t); return __builtin_bit_cast(unsigned, b); }
; template <int MODE> __device__ __forceinline__ void norm_phase(const Ptrs& P, const float* nw, int gw, int NGW, int lane) {
;     ...
;         ss = wave_sum(ss, lane);
;         const float rstd = 1.0f / sqrtf(ss * (1.0f / DM) + EPS);
;         if (MODE == 1) {
; #pragma unroll
;             for (int j = 0; j < 8; ++j) { u32x2 w; w.x = pk2(v[j][0], v[j][1]); w.y = pk2(v[j][2], v[j][3]); pg8::store8_wt((u32x2*)(H + (size_t)row * DM) + 64 * j + lane, w); }
;         }
; #pragma unroll
;         for (int j = 0; j < 8; ++j) {
;             const f32x4 w4 = ((const f32x4*)nw)[64 * j + lane];
;             const f32x4 o = v[j] * rstd * w4;
;             if (MODE == 2) ((f32x4*)(P.out + (size_t)row * DM))[64 * j + lane] = o;
;             else { u32x2 w; w.x = pk2(o[0], o[1]); w.y = pk2(o[2], o[3]); pg8::store8_wt((u32x2*)(U + (size_t)row * DM) + 64 * j + lane, w); }
;         }
	v_add_f32_e32 v43, v43, v44
	ds_bpermute_b32 v44, v66, v43
	s_waitcnt lgkmcnt(0)
	v_add_f32_e32 v43, v43, v44
	ds_bpermute_b32 v44, v67, v43
	s_waitcnt lgkmcnt(0)
	v_add_f32_e32 v43, v43, v44
	ds_bpermute_b32 v44, v68, v43
	s_waitcnt lgkmcnt(0)
	v_add_f32_e32 v43, v43, v44
	ds_bpermute_b32 v44, v69, v43
	s_waitcnt lgkmcnt(0)
	v_add_f32_e32 v43, v43, v44
	ds_bpermute_b32 v44, v70, v43
	s_waitcnt lgkmcnt(0)
	v_add_f32_e32 v43, v43, v44
	v_fmamk_f32 v43, v43, 0x3a000000, v64
	v_mul_f32_e32 v44, 0x4f800000, v43
	v_cmp_gt_f32_e32 vcc, s12, v43
	s_nop 1
	v_cndmask_b32_e32 v43, v43, v44, vcc
	v_sqrt_f32_e32 v44, v43
	s_nop 0
	v_add_u32_e32 v45, -1, v44
	v_fma_f32 v63, -v45, v44, v43
	v_cmp_ge_f32_e64 s[2:3], 0, v63
	v_add_u32_e32 v63, 1, v44
	s_nop 0
	v_cndmask_b32_e64 v45, v44, v45, s[2:3]
	v_fma_f32 v44, -v63, v44, v43
	v_cmp_lt_f32_e64 s[2:3], 0, v44
	s_nop 1
	v_cndmask_b32_e64 v44, v45, v63, s[2:3]
	v_mul_f32_e32 v45, 0x37800000, v44
	v_cndmask_b32_e32 v44, v44, v45, vcc
	v_cmp_class_f32_e32 vcc, v43, v65
	s_nop 1
	v_cndmask_b32_e32 v43, v44, v43, vcc
	v_div_scale_f32 v44, s[2:3], v43, v43, 1.0
	v_rcp_f32_e32 v45, v44
	s_nop 0
	v_fma_f32 v63, -v44, v45, 1.0
	v_fmac_f32_e32 v45, v63, v45
	v_div_scale_f32 v63, vcc, 1.0, v43, 1.0
	v_mul_f32_e32 v78, v63, v45
	v_fma_f32 v80, -v44, v78, v63
	v_fmac_f32_e32 v78, v80, v45
	v_fma_f32 v44, -v44, v78, v63
	v_div_fmas_f32 v44, v44, v45, v78
	v_div_fixup_f32 v78, v44, v43, 1.0
	v_mov_b32_e32 v44, v55
	v_mov_b32_e32 v45, v57
	v_mov_b32_e32 v80, v61
	v_pk_mul_f32 v[44:45], v[44:45], v[78:79] op_sel_hi:[1,0]
	v_pk_mul_f32 v[80:81], v[80:81], v[78:79] op_sel_hi:[1,0]
	s_nop 0
	v_pk_mul_f32 v[72:73], v[100:101], v[44:45]
	v_pk_mul_f32 v[74:75], v[102:103], v[80:81]
	global_store_dwordx4 v[12:13], v[72:75], off offset:-4096
	s_nop 0
	v_mov_b32_e32 v61, v76
	v_mov_b32_e32 v55, v56
	v_pk_mul_f32 v[44:45], v[60:61], v[78:79] op_sel_hi:[1,0]
	v_pk_mul_f32 v[54:55], v[54:55], v[78:79] op_sel_hi:[1,0]
	v_pk_mul_f32 v[48:49], v[48:49], v[78:79] op_sel_hi:[1,0]
	v_mov_b32_e32 v63, v71
	v_pk_mul_f32 v[34:35], v[34:35], v[78:79] op_sel_hi:[1,0]
	v_pk_mul_f32 v[32:33], v[32:33], v[78:79] op_sel_hi:[1,0]
	v_mov_b32_e32 v43, v79
	s_nop 0
	v_pk_mul_f32 v[54:55], v[104:105], v[54:55]
	v_pk_mul_f32 v[56:57], v[106:107], v[44:45]
	global_store_dwordx4 v[12:13], v[54:57], off offset:-3072
	s_nop 0
	v_mov_b32_e32 v44, v51
	v_mov_b32_e32 v45, v53
	v_mov_b32_e32 v51, v52
	v_pk_mul_f32 v[44:45], v[78:79], v[44:45] op_sel_hi:[0,1]
	v_pk_mul_f32 v[50:51], v[78:79], v[50:51] op_sel_hi:[0,1]
	s_nop 0
	v_pk_mul_f32 v[50:51], v[108:109], v[50:51]
	v_pk_mul_f32 v[52:53], v[110:111], v[44:45]
	global_store_dwordx4 v[12:13], v[50:53], off offset:-2048
	s_nop 0
	v_pk_mul_f32 v[44:45], v[46:47], v[78:79] op_sel_hi:[1,0]
	s_nop 0
	v_pk_mul_f32 v[46:47], v[114:115], v[48:49]
	v_pk_mul_f32 v[44:45], v[112:113], v[44:45]
	global_store_dwordx4 v[12:13], v[44:47], off offset:-1024
	s_nop 0
	v_pk_mul_f32 v[48:49], v[58:59], v[78:79] op_sel_hi:[1,0]
	v_pk_mul_f32 v[50:51], v[62:63], v[78:79] op_sel_hi:[1,0]
	v_pk_mul_f32 v[52:53], v[40:41], v[78:79] op_sel_hi:[1,0]
	v_pk_mul_f32 v[40:41], v[42:43], v[78:79] op_sel_hi:[1,0]
	s_waitcnt vmcnt(4)
	v_mov_b64_e32 v[62:63], v[20:21]
	s_nop 0
	v_pk_mul_f32 v[44:45], v[50:51], v[116:117]
	v_pk_mul_f32 v[46:47], v[48:49], v[118:119]
	global_store_dwordx4 v[12:13], v[44:47], off
	s_nop 0
	v_mov_b32_e32 v48, v37
	v_mov_b32_e32 v49, v39
	v_mov_b32_e32 v37, v38
	v_pk_mul_f32 v[38:39], v[78:79], v[48:49] op_sel_hi:[0,1]
	v_pk_mul_f32 v[36:37], v[78:79], v[36:37] op_sel_hi:[0,1]
	s_nop 0
	v_pk_mul_f32 v[36:37], v[36:37], v[120:121]
	v_pk_mul_f32 v[38:39], v[38:39], v[122:123]
	global_store_dwordx4 v[12:13], v[36:39], off offset:1024
	s_nop 0
	v_mov_b64_e32 v[44:45], v[30:31]
	v_mov_b64_e32 v[46:47], v[26:27]
	s_nop 0
	v_pk_mul_f32 v[32:33], v[32:33], v[124:125]
	v_pk_mul_f32 v[34:35], v[34:35], v[126:127]
	global_store_dwordx4 v[12:13], v[32:35], off offset:2048
	s_nop 0
	v_mov_b64_e32 v[36:37], v[22:23]
	v_mov_b64_e32 v[34:35], v[16:17]
	v_mov_b64_e32 v[32:33], v[18:19]
	v_mov_b64_e32 v[38:39], v[24:25]
	s_nop 0
	v_pk_mul_f32 v[40:41], v[40:41], v[128:129]
	v_pk_mul_f32 v[42:43], v[52:53], v[130:131]
	global_store_dwordx4 v[12:13], v[40:43], off offset:3072
	v_lshl_add_u64 v[12:13], v[12:13], 0, s[8:9]
	s_nop 0
	v_mov_b64_e32 v[40:41], v[28:29]
	s_andn2_b64 exec, exec, s[4:5]
	s_cbranch_execz .LBB0_1718
